# grid barrier: non-leader release poll interval s_sleep 1 -> s_sleep 8 (less traffic on the shared arrival counter); on v36
# speedup vs baseline: 1.0053x; 1.0053x over previous
.LBB0_333:
	s_and_b32 s20, s27, 0xff
	s_mov_b64 s[18:19], -1
	s_cmp_lg_u32 s20, 0
	s_mov_b64 s[20:21], -1
	s_sleep 8
	s_cbranch_scc1 .LBB0_337
	v_mov_b64_e32 v[2:3], s[4:5]
	flat_load_dword v2, v[2:3] offset:512 sc1
	s_mov_b64 s[20:21], 0
	s_mov_b64 s[22:23], -1
	s_waitcnt vmcnt(0) lgkmcnt(0)
	v_cmp_eq_u32_e32 vcc, 0, v2
	s_and_saveexec_b64 s[24:25], vcc
	s_cmp_lt_u32 s27, 0x400001
	s_cselect_b64 s[20:21], -1, 0
	s_xor_b64 s[22:23], exec, -1
	s_and_b64 s[20:21], s[20:21], exec
	s_or_b64 exec, exec, s[24:25]
